# branch-merge GEMM epilogue: the 16 gate loads of a row half issued back to back as global loads with one wait (were 8 serialized round trips)
# speedup vs baseline: 1.0548x; 1.0168x over previous
.LBB0_211:
	s_add_u32 s18, s16, 0xfffe0080
	s_addc_u32 s19, s17, -1
	s_add_i32 s42, 0, 0x10000
	v_add_u32_e32 v12, s42, v241
	ds_read_b128 v[0:3], v12
	ds_read_b128 v[4:7], v12 offset:1024
	ds_read_b128 v[8:11], v12 offset:2048
	ds_read_b128 v[12:15], v12 offset:3072
	s_cmp_eq_u32 s41, 4
	s_cselect_b32 s23, s2, s19
	s_cselect_b32 s22, s9, s18
	s_cselect_b32 s19, s12, s40
	s_cselect_b32 s18, s15, s34
	v_lshl_add_u64 v[178:179], s[16:17], 0, v[216:217]
	s_add_i32 m0, s52, 0xc000
	ds_read_b128 v[146:149], v243
	ds_read_b128 v[150:153], v243 offset:1024
	ds_read_b128 v[154:157], v243 offset:2048
	ds_read_b128 v[158:161], v243 offset:3072
	ds_read_b128 v[162:165], v243 offset:4096
	ds_read_b128 v[166:169], v243 offset:5120
	ds_read_b128 v[170:173], v243 offset:6144
	ds_read_b128 v[174:177], v243 offset:7168
	global_load_lds_dwordx4 v[178:179], off
	v_lshl_add_u64 v[178:179], s[16:17], 0, v[214:215]
	s_add_i32 m0, s52, 0xe000
	s_nop 0
	global_load_lds_dwordx4 v[178:179], off
	s_waitcnt lgkmcnt(8)
	s_barrier
	s_waitcnt lgkmcnt(0)
	s_setprio 1
	s_waitcnt lgkmcnt(0)
	v_mfma_f32_16x16x32_bf16 v[142:145], v[0:3], v[146:149], v[142:145]
	v_mfma_f32_16x16x32_bf16 v[138:141], v[8:11], v[146:149], v[138:141]
	v_mfma_f32_16x16x32_bf16 v[134:137], v[0:3], v[154:157], v[134:137]
	v_mfma_f32_16x16x32_bf16 v[130:133], v[8:11], v[154:157], v[130:133]
	v_mfma_f32_16x16x32_bf16 v[126:129], v[0:3], v[162:165], v[126:129]
	v_mfma_f32_16x16x32_bf16 v[122:125], v[8:11], v[162:165], v[122:125]
	v_mfma_f32_16x16x32_bf16 v[118:121], v[0:3], v[170:173], v[118:121]
	v_mfma_f32_16x16x32_bf16 v[114:117], v[8:11], v[170:173], v[114:117]
	v_mfma_f32_16x16x32_bf16 v[142:145], v[4:7], v[150:153], v[142:145]
	v_mfma_f32_16x16x32_bf16 v[138:141], v[12:15], v[150:153], v[138:141]
	v_mfma_f32_16x16x32_bf16 v[134:137], v[4:7], v[158:161], v[134:137]
	v_mfma_f32_16x16x32_bf16 v[130:133], v[12:15], v[158:161], v[130:133]
	v_mfma_f32_16x16x32_bf16 v[126:129], v[4:7], v[166:169], v[126:129]
	v_mfma_f32_16x16x32_bf16 v[122:125], v[12:15], v[166:169], v[122:125]
	v_mfma_f32_16x16x32_bf16 v[118:121], v[4:7], v[174:177], v[118:121]
	v_mfma_f32_16x16x32_bf16 v[114:117], v[12:15], v[174:177], v[114:117]
	s_setprio 0
	s_barrier
	s_add_i32 s55, 0, 0x14000
	s_add_i32 s42, s42, s49
	v_add_u32_e32 v190, s55, v241
	v_lshl_add_u64 v[194:195], s[18:19], 0, v[16:17]
	s_mov_b32 m0, s42
	ds_read_b128 v[178:181], v190
	ds_read_b128 v[182:185], v190 offset:1024
	ds_read_b128 v[186:189], v190 offset:2048
	ds_read_b128 v[190:193], v190 offset:3072
	global_load_lds_dwordx4 v[194:195], off
	v_lshl_add_u64 v[196:197], s[18:19], 0, v[212:213]
	s_add_i32 m0, s42, 0x2000
	s_nop 0
	global_load_lds_dwordx4 v[196:197], off
	s_barrier
	s_waitcnt lgkmcnt(0)
	s_setprio 1
	s_waitcnt lgkmcnt(0)
	v_mfma_f32_16x16x32_bf16 v[110:113], v[178:181], v[146:149], v[110:113]
	v_mfma_f32_16x16x32_bf16 v[106:109], v[186:189], v[146:149], v[106:109]
	v_mfma_f32_16x16x32_bf16 v[102:105], v[178:181], v[154:157], v[102:105]
	v_mfma_f32_16x16x32_bf16 v[98:101], v[186:189], v[154:157], v[98:101]
	v_mfma_f32_16x16x32_bf16 v[94:97], v[178:181], v[162:165], v[94:97]
	v_mfma_f32_16x16x32_bf16 v[90:93], v[186:189], v[162:165], v[90:93]
	v_mfma_f32_16x16x32_bf16 v[86:89], v[178:181], v[170:173], v[86:89]
	v_mfma_f32_16x16x32_bf16 v[82:85], v[186:189], v[170:173], v[82:85]
	v_mfma_f32_16x16x32_bf16 v[110:113], v[182:185], v[150:153], v[110:113]
	v_mfma_f32_16x16x32_bf16 v[106:109], v[190:193], v[150:153], v[106:109]
	v_mfma_f32_16x16x32_bf16 v[102:105], v[182:185], v[158:161], v[102:105]
	v_mfma_f32_16x16x32_bf16 v[98:101], v[190:193], v[158:161], v[98:101]
	v_mfma_f32_16x16x32_bf16 v[94:97], v[182:185], v[166:169], v[94:97]
	v_mfma_f32_16x16x32_bf16 v[90:93], v[190:193], v[166:169], v[90:93]
	v_mfma_f32_16x16x32_bf16 v[86:89], v[182:185], v[174:177], v[86:89]
	v_mfma_f32_16x16x32_bf16 v[82:85], v[190:193], v[174:177], v[82:85]
	s_setprio 0
	s_mov_b32 m0, s52
	v_lshl_add_u64 v[218:219], s[22:23], 0, v[208:209]
	s_barrier
	ds_read_b128 v[146:149], v243 offset:16384
	ds_read_b128 v[150:153], v243 offset:17408
	ds_read_b128 v[154:157], v243 offset:18432
	ds_read_b128 v[158:161], v243 offset:19456
	ds_read_b128 v[162:165], v243 offset:20480
	ds_read_b128 v[166:169], v243 offset:21504
	ds_read_b128 v[170:173], v243 offset:22528
	ds_read_b128 v[174:177], v243 offset:23552
	global_load_lds_dwordx4 v[218:219], off
	v_lshl_add_u64 v[220:221], s[22:23], 0, v[210:211]
	s_mov_b32 m0, s58
	s_nop 0
	global_load_lds_dwordx4 v[220:221], off
	s_barrier
	s_waitcnt lgkmcnt(0)
	s_setprio 1
	s_waitcnt lgkmcnt(0)
	v_mfma_f32_16x16x32_bf16 v[78:81], v[0:3], v[146:149], v[78:81]
	v_mfma_f32_16x16x32_bf16 v[74:77], v[8:11], v[146:149], v[74:77]
	v_mfma_f32_16x16x32_bf16 v[70:73], v[0:3], v[154:157], v[70:73]
	v_mfma_f32_16x16x32_bf16 v[66:69], v[8:11], v[154:157], v[66:69]
	v_mfma_f32_16x16x32_bf16 v[62:65], v[0:3], v[162:165], v[62:65]
	v_mfma_f32_16x16x32_bf16 v[58:61], v[8:11], v[162:165], v[58:61]
	v_mfma_f32_16x16x32_bf16 v[0:3], v[0:3], v[170:173], v[54:57]
	v_mfma_f32_16x16x32_bf16 v[78:81], v[4:7], v[150:153], v[78:81]
	v_mfma_f32_16x16x32_bf16 v[74:77], v[12:15], v[150:153], v[74:77]
	v_mfma_f32_16x16x32_bf16 v[70:73], v[4:7], v[158:161], v[70:73]
	v_mfma_f32_16x16x32_bf16 v[66:69], v[12:15], v[158:161], v[66:69]
	v_mfma_f32_16x16x32_bf16 v[62:65], v[4:7], v[166:169], v[62:65]
	v_mfma_f32_16x16x32_bf16 v[58:61], v[12:15], v[166:169], v[58:61]
	v_mfma_f32_16x16x32_bf16 v[0:3], v[4:7], v[174:177], v[0:3]
	v_mfma_f32_16x16x32_bf16 v[4:7], v[8:11], v[170:173], v[50:53]
	v_mfma_f32_16x16x32_bf16 v[4:7], v[12:15], v[174:177], v[4:7]
	s_setprio 0
	s_barrier
	s_add_u32 s42, s18, 0x20000
	s_addc_u32 s43, s19, 0
	s_add_i32 s55, s55, s49
	v_lshl_add_u64 v[8:9], s[42:43], 0, v[16:17]
	s_mov_b32 m0, s55
	s_nop 0
	global_load_lds_dwordx4 v[8:9], off
	v_lshl_add_u64 v[8:9], s[42:43], 0, v[212:213]
	s_add_i32 m0, s55, 0x2000
	s_nop 0
	global_load_lds_dwordx4 v[8:9], off
	s_waitcnt vmcnt(6)
	s_barrier
	s_setprio 1
	v_mfma_f32_16x16x32_bf16 v[38:41], v[178:181], v[154:157], v[38:41]
	v_mfma_f32_16x16x32_bf16 v[34:37], v[186:189], v[154:157], v[34:37]
	v_mfma_f32_16x16x32_bf16 v[30:33], v[178:181], v[162:165], v[30:33]
	v_mfma_f32_16x16x32_bf16 v[26:29], v[186:189], v[162:165], v[26:29]
	v_mfma_f32_16x16x32_bf16 v[22:25], v[178:181], v[170:173], v[22:25]
	v_mfma_f32_16x16x32_bf16 v[18:21], v[186:189], v[170:173], v[18:21]
	v_mfma_f32_16x16x32_bf16 v[8:11], v[178:181], v[146:149], v[46:49]
	v_mfma_f32_16x16x32_bf16 v[12:15], v[186:189], v[146:149], v[42:45]
	v_mfma_f32_16x16x32_bf16 v[38:41], v[182:185], v[158:161], v[38:41]
	v_mfma_f32_16x16x32_bf16 v[34:37], v[190:193], v[158:161], v[34:37]
	v_mfma_f32_16x16x32_bf16 v[30:33], v[182:185], v[166:169], v[30:33]
	v_mfma_f32_16x16x32_bf16 v[26:29], v[190:193], v[166:169], v[26:29]
	v_mfma_f32_16x16x32_bf16 v[22:25], v[182:185], v[174:177], v[22:25]
	v_mfma_f32_16x16x32_bf16 v[18:21], v[190:193], v[174:177], v[18:21]
	v_mfma_f32_16x16x32_bf16 v[8:11], v[182:185], v[150:153], v[8:11]
	v_mfma_f32_16x16x32_bf16 v[12:15], v[190:193], v[150:153], v[12:15]
	s_setprio 0
	s_add_i32 s42, 0, 0x18000
	v_add_u32_e32 v54, s42, v241
	s_barrier
	ds_read_b128 v[42:45], v54
	ds_read_b128 v[46:49], v54 offset:1024
	ds_read_b128 v[50:53], v54 offset:2048
	ds_read_b128 v[146:149], v54 offset:3072
	s_add_u32 s22, s22, 0x20000
	s_addc_u32 s23, s23, 0
	s_mov_b32 m0, s59
	v_lshl_add_u64 v[178:179], s[22:23], 0, v[208:209]
	ds_read_b128 v[54:57], v243 offset:32768
	ds_read_b128 v[150:153], v243 offset:33792
	ds_read_b128 v[154:157], v243 offset:34816
	ds_read_b128 v[158:161], v243 offset:35840
	ds_read_b128 v[162:165], v243 offset:36864
	ds_read_b128 v[166:169], v243 offset:37888
	ds_read_b128 v[170:173], v243 offset:38912
	ds_read_b128 v[174:177], v243 offset:39936
	global_load_lds_dwordx4 v[178:179], off
	v_lshl_add_u64 v[178:179], s[22:23], 0, v[210:211]
	s_mov_b32 m0, s60
	s_nop 0
	global_load_lds_dwordx4 v[178:179], off
	s_waitcnt lgkmcnt(8)
	s_barrier
	s_waitcnt lgkmcnt(0)
	s_setprio 1
	s_waitcnt lgkmcnt(0)
	v_mfma_f32_16x16x32_bf16 v[142:145], v[42:45], v[54:57], v[142:145]
	v_mfma_f32_16x16x32_bf16 v[138:141], v[50:53], v[54:57], v[138:141]
	v_mfma_f32_16x16x32_bf16 v[134:137], v[42:45], v[154:157], v[134:137]
	v_mfma_f32_16x16x32_bf16 v[130:133], v[50:53], v[154:157], v[130:133]
	v_mfma_f32_16x16x32_bf16 v[126:129], v[42:45], v[162:165], v[126:129]
	v_mfma_f32_16x16x32_bf16 v[122:125], v[50:53], v[162:165], v[122:125]
	v_mfma_f32_16x16x32_bf16 v[118:121], v[42:45], v[170:173], v[118:121]
	v_mfma_f32_16x16x32_bf16 v[114:117], v[50:53], v[170:173], v[114:117]
	v_mfma_f32_16x16x32_bf16 v[142:145], v[46:49], v[150:153], v[142:145]
	v_mfma_f32_16x16x32_bf16 v[138:141], v[146:149], v[150:153], v[138:141]
	v_mfma_f32_16x16x32_bf16 v[134:137], v[46:49], v[158:161], v[134:137]
	v_mfma_f32_16x16x32_bf16 v[130:133], v[146:149], v[158:161], v[130:133]
	v_mfma_f32_16x16x32_bf16 v[126:129], v[46:49], v[166:169], v[126:129]
	v_mfma_f32_16x16x32_bf16 v[122:125], v[146:149], v[166:169], v[122:125]
	v_mfma_f32_16x16x32_bf16 v[118:121], v[46:49], v[174:177], v[118:121]
	v_mfma_f32_16x16x32_bf16 v[114:117], v[146:149], v[174:177], v[114:117]
	s_setprio 0
	s_barrier
	s_add_i32 s22, 0, 0x1c000
	s_add_i32 s23, s42, s49
	v_add_u32_e32 v190, s22, v241
	v_lshl_add_u64 v[194:195], v[194:195], 0, s[10:11]
	s_mov_b32 m0, s23
	ds_read_b128 v[178:181], v190
	ds_read_b128 v[182:185], v190 offset:1024
	ds_read_b128 v[186:189], v190 offset:2048
	ds_read_b128 v[190:193], v190 offset:3072
	global_load_lds_dwordx4 v[194:195], off
	v_lshl_add_u64 v[194:195], v[196:197], 0, s[10:11]
	s_add_i32 m0, s23, 0x2000
	s_nop 0
	global_load_lds_dwordx4 v[194:195], off
	s_barrier
	s_waitcnt lgkmcnt(0)
	s_setprio 1
	s_waitcnt lgkmcnt(0)
	v_mfma_f32_16x16x32_bf16 v[110:113], v[178:181], v[54:57], v[110:113]
	v_mfma_f32_16x16x32_bf16 v[54:57], v[186:189], v[54:57], v[106:109]
	v_mfma_f32_16x16x32_bf16 v[106:109], v[190:193], v[150:153], v[54:57]
	v_mfma_f32_16x16x32_bf16 v[54:57], v[178:181], v[154:157], v[102:105]
	v_mfma_f32_16x16x32_bf16 v[102:105], v[182:185], v[158:161], v[54:57]
	v_mfma_f32_16x16x32_bf16 v[54:57], v[186:189], v[154:157], v[98:101]
	v_mfma_f32_16x16x32_bf16 v[98:101], v[190:193], v[158:161], v[54:57]
	v_mfma_f32_16x16x32_bf16 v[54:57], v[178:181], v[162:165], v[94:97]
	v_mfma_f32_16x16x32_bf16 v[94:97], v[182:185], v[166:169], v[54:57]
	v_mfma_f32_16x16x32_bf16 v[54:57], v[186:189], v[162:165], v[90:93]
	v_mfma_f32_16x16x32_bf16 v[90:93], v[190:193], v[166:169], v[54:57]
	v_mfma_f32_16x16x32_bf16 v[54:57], v[178:181], v[170:173], v[86:89]
	v_mfma_f32_16x16x32_bf16 v[86:89], v[182:185], v[174:177], v[54:57]
	v_mfma_f32_16x16x32_bf16 v[54:57], v[186:189], v[170:173], v[82:85]
	v_mfma_f32_16x16x32_bf16 v[110:113], v[182:185], v[150:153], v[110:113]
	v_mfma_f32_16x16x32_bf16 v[82:85], v[190:193], v[174:177], v[54:57]
	s_setprio 0
	s_mov_b32 m0, s61
	s_nop 3
	v_lshl_add_u64 v[54:55], v[218:219], 0, s[10:11]
	s_barrier
	ds_read_b128 v[150:153], v243 offset:49152
	ds_read_b128 v[154:157], v243 offset:50176
	ds_read_b128 v[158:161], v243 offset:51200
	ds_read_b128 v[162:165], v243 offset:52224
	ds_read_b128 v[166:169], v243 offset:53248
	ds_read_b128 v[170:173], v243 offset:54272
	ds_read_b128 v[174:177], v243 offset:55296
	ds_read_b128 v[194:197], v243 offset:56320
	global_load_lds_dwordx4 v[54:55], off
	v_lshl_add_u64 v[54:55], v[220:221], 0, s[10:11]
	s_mov_b32 m0, s35
	s_nop 0
	global_load_lds_dwordx4 v[54:55], off
	s_barrier
	s_waitcnt lgkmcnt(0)
	s_setprio 1
	s_waitcnt lgkmcnt(0)
	v_mfma_f32_16x16x32_bf16 v[54:57], v[42:45], v[150:153], v[78:81]
	v_mfma_f32_16x16x32_bf16 v[78:81], v[46:49], v[154:157], v[54:57]
	v_mfma_f32_16x16x32_bf16 v[54:57], v[50:53], v[150:153], v[74:77]
	v_mfma_f32_16x16x32_bf16 v[74:77], v[146:149], v[154:157], v[54:57]
	v_mfma_f32_16x16x32_bf16 v[54:57], v[42:45], v[158:161], v[70:73]
	v_mfma_f32_16x16x32_bf16 v[70:73], v[46:49], v[162:165], v[54:57]
	v_mfma_f32_16x16x32_bf16 v[54:57], v[50:53], v[158:161], v[66:69]
	v_mfma_f32_16x16x32_bf16 v[66:69], v[146:149], v[162:165], v[54:57]
	v_mfma_f32_16x16x32_bf16 v[54:57], v[42:45], v[166:169], v[62:65]
	v_mfma_f32_16x16x32_bf16 v[62:65], v[46:49], v[170:173], v[54:57]
	v_mfma_f32_16x16x32_bf16 v[54:57], v[50:53], v[166:169], v[58:61]
	v_mfma_f32_16x16x32_bf16 v[0:3], v[42:45], v[174:177], v[0:3]
	v_mfma_f32_16x16x32_bf16 v[58:61], v[146:149], v[170:173], v[54:57]
	v_mfma_f32_16x16x32_bf16 v[54:57], v[46:49], v[194:197], v[0:3]
	v_mfma_f32_16x16x32_bf16 v[0:3], v[50:53], v[174:177], v[4:7]
	v_mfma_f32_16x16x32_bf16 v[50:53], v[146:149], v[194:197], v[0:3]
	s_setprio 0
	s_barrier
	s_add_u32 s18, s18, 0x20080
	s_addc_u32 s19, s19, 0
	s_add_i32 s22, s22, s49
	s_nop 1
	v_lshl_add_u64 v[0:1], s[18:19], 0, v[16:17]
	s_mov_b32 m0, s22
	s_nop 0
	global_load_lds_dwordx4 v[0:1], off
	v_lshl_add_u64 v[0:1], s[18:19], 0, v[212:213]
	s_add_i32 m0, s22, 0x2000
	s_nop 0
	global_load_lds_dwordx4 v[0:1], off
	s_waitcnt vmcnt(6)
	s_barrier
	s_setprio 1
	v_mfma_f32_16x16x32_bf16 v[0:3], v[178:181], v[150:153], v[8:11]
	v_mfma_f32_16x16x32_bf16 v[46:49], v[182:185], v[154:157], v[0:3]
	v_mfma_f32_16x16x32_bf16 v[0:3], v[186:189], v[150:153], v[12:15]
	v_mfma_f32_16x16x32_bf16 v[42:45], v[190:193], v[154:157], v[0:3]
	v_mfma_f32_16x16x32_bf16 v[0:3], v[178:181], v[158:161], v[38:41]
	v_mfma_f32_16x16x32_bf16 v[38:41], v[182:185], v[162:165], v[0:3]
	v_mfma_f32_16x16x32_bf16 v[0:3], v[186:189], v[158:161], v[34:37]
	v_mfma_f32_16x16x32_bf16 v[34:37], v[190:193], v[162:165], v[0:3]
	v_mfma_f32_16x16x32_bf16 v[0:3], v[178:181], v[166:169], v[30:33]
	v_mfma_f32_16x16x32_bf16 v[30:33], v[182:185], v[170:173], v[0:3]
	v_mfma_f32_16x16x32_bf16 v[0:3], v[186:189], v[166:169], v[26:29]
	v_mfma_f32_16x16x32_bf16 v[26:29], v[190:193], v[170:173], v[0:3]
	v_mfma_f32_16x16x32_bf16 v[0:3], v[178:181], v[174:177], v[22:25]
	v_mfma_f32_16x16x32_bf16 v[22:25], v[182:185], v[194:197], v[0:3]
	v_mfma_f32_16x16x32_bf16 v[0:3], v[186:189], v[174:177], v[18:21]
	v_mfma_f32_16x16x32_bf16 v[18:21], v[190:193], v[194:197], v[0:3]
	s_setprio 0
	s_add_i32 s41, s41, 2
	s_add_u32 s34, s34, 0x100
	s_addc_u32 s40, s40, 0
	s_add_u32 s16, s16, 0x100
	s_addc_u32 s17, s17, 0
	s_cmp_gt_u32 s41, 5
	s_barrier
	s_cbranch_scc0 .LBB0_211
	s_cmp_eq_u32 s84, 3
	s_cselect_b64 s[16:17], -1, 0
	s_cmp_lg_u32 s84, 3
	v_lshl_add_u32 v220, s8, 8, v240
	v_lshl_or_b32 v218, s14, 8, v242
	s_cselect_b64 s[8:9], -1, 0
	s_lshl_b32 s14, s84, 10
	v_mov_b64_e32 v[0:1], s[94:95]
	s_ashr_i32 s15, s14, 31
	v_mad_i64_i32 v[0:1], s[18:19], v220, s66, v[0:1]
	v_ashrrev_i32_e32 v219, 31, v218
	v_lshl_add_u64 v[0:1], s[14:15], 1, v[0:1]
	v_lshl_add_u64 v[4:5], v[218:219], 1, v[0:1]
	v_add_co_u32_e32 v0, vcc, 0x2000, v4
	s_mov_b64 s[18:19], 0x2400
	s_nop 0
	v_addc_co_u32_e32 v1, vcc, 0, v5, vcc
	global_load_dwordx4 v[0:3], v[0:1], off offset:1024
	s_and_b64 vcc, exec, s[16:17]
	v_lshl_add_u64 v[4:5], v[4:5], 0, s[18:19]
	s_cbranch_vccnz .LBB0_214
	global_load_dwordx4 v[12:15], v[4:5], off offset:2048
.LBB0_214:
	global_load_dwordx4 v[8:11], v[4:5], off offset:256
	v_cndmask_b32_e64 v6, 0, 1, s[8:9]
	v_cmp_ne_u32_e64 s[40:41], 1, v6
	s_andn2_b64 vcc, exec, s[8:9]
	v_readlane_b32 s91, v255, 7
	s_cbranch_vccnz .LBB0_216
	global_load_dwordx4 v[194:197], v[4:5], off offset:2304
.LBB0_216:
	v_or_b32_e32 v226, 16, v220
	v_mov_b64_e32 v[4:5], s[94:95]
	v_mad_i64_i32 v[4:5], s[18:19], v226, s66, v[4:5]
	v_lshl_add_u64 v[4:5], s[14:15], 1, v[4:5]
	v_lshl_add_u64 v[4:5], v[218:219], 1, v[4:5]
	v_add_co_u32_e32 v6, vcc, 0x2000, v4
	s_mov_b64 s[18:19], 0x2400
	s_nop 0
	v_addc_co_u32_e32 v7, vcc, 0, v5, vcc
	global_load_dwordx4 v[190:193], v[6:7], off offset:1024
	v_ashrrev_i32_e32 v221, 31, v220
	v_lshl_add_u64 v[4:5], v[4:5], 0, s[18:19]
	s_and_b64 vcc, exec, s[40:41]
	s_cbranch_vccnz .LBB0_218
	global_load_dwordx4 v[186:189], v[4:5], off offset:2048
.LBB0_218:
	global_load_dwordx4 v[182:185], v[4:5], off offset:256
	s_and_b64 vcc, exec, s[40:41]
	s_cbranch_vccnz .LBB0_220
	global_load_dwordx4 v[178:181], v[4:5], off offset:2304
.LBB0_220:
	v_or_b32_e32 v224, 32, v220
	v_mov_b64_e32 v[4:5], s[94:95]
	v_mad_i64_i32 v[4:5], s[18:19], v224, s66, v[4:5]
	v_lshl_add_u64 v[4:5], s[14:15], 1, v[4:5]
	v_lshl_add_u64 v[4:5], v[218:219], 1, v[4:5]
	v_add_co_u32_e32 v6, vcc, 0x2000, v4
	s_mov_b64 s[18:19], 0x2400
	s_nop 0
	v_addc_co_u32_e32 v7, vcc, 0, v5, vcc
	global_load_dwordx4 v[174:177], v[6:7], off offset:1024
	v_lshl_add_u64 v[4:5], v[4:5], 0, s[18:19]
	s_and_b64 vcc, exec, s[40:41]
	s_cbranch_vccnz .LBB0_222
	global_load_dwordx4 v[170:173], v[4:5], off offset:2048
.LBB0_222:
	global_load_dwordx4 v[166:169], v[4:5], off offset:256
	s_and_b64 vcc, exec, s[40:41]
	s_cbranch_vccnz .LBB0_224
	global_load_dwordx4 v[162:165], v[4:5], off offset:2304
.LBB0_224:
	v_or_b32_e32 v222, 48, v220
	v_mov_b64_e32 v[4:5], s[94:95]
	v_mad_i64_i32 v[4:5], s[18:19], v222, s66, v[4:5]
	v_lshl_add_u64 v[4:5], s[14:15], 1, v[4:5]
	v_lshl_add_u64 v[4:5], v[218:219], 1, v[4:5]
	v_add_co_u32_e32 v6, vcc, 0x2000, v4
	s_mov_b64 s[18:19], 0x2400
	s_nop 0
	v_addc_co_u32_e32 v7, vcc, 0, v5, vcc
	global_load_dwordx4 v[158:161], v[6:7], off offset:1024
	v_lshl_add_u64 v[4:5], v[4:5], 0, s[18:19]
	s_and_b64 vcc, exec, s[40:41]
	s_cbranch_vccnz .LBB0_226
	global_load_dwordx4 v[154:157], v[4:5], off offset:2048
.LBB0_226:
	global_load_dwordx4 v[150:153], v[4:5], off offset:256
	s_and_b64 vcc, exec, s[40:41]
	s_cbranch_vccnz .LBB0_228
	global_load_dwordx4 v[146:149], v[4:5], off offset:2304
.LBB0_228:
	s_waitcnt vmcnt(0) lgkmcnt(0)
	s_and_b64 vcc, exec, s[40:41]
	s_cbranch_vccz .Lbr_gate_a
	v_mov_b64_e32 v[14:15], v[2:3]
	v_mov_b64_e32 v[12:13], v[0:1]
	v_mov_b64_e32 v[196:197], v[10:11]
	v_mov_b64_e32 v[194:195], v[8:9]
	v_mov_b64_e32 v[186:187], v[190:191]
	v_mov_b64_e32 v[188:189], v[192:193]
	v_mov_b64_e32 v[178:179], v[182:183]
	v_mov_b64_e32 v[180:181], v[184:185]
	v_mov_b64_e32 v[170:171], v[174:175]
	v_mov_b64_e32 v[172:173], v[176:177]
	v_mov_b64_e32 v[162:163], v[166:167]
	v_mov_b64_e32 v[164:165], v[168:169]
	v_mov_b64_e32 v[154:155], v[158:159]
	v_mov_b64_e32 v[156:157], v[160:161]
	v_mov_b64_e32 v[146:147], v[150:151]
	v_mov_b64_e32 v[148:149], v[152:153]

.LBB0_268:
	v_add_u32_e32 v226, 0x80, v220
	v_mov_b64_e32 v[0:1], s[94:95]
	v_mad_i64_i32 v[0:1], s[16:17], v226, s66, v[0:1]
	v_lshl_add_u64 v[0:1], s[14:15], 1, v[0:1]
	v_lshl_add_u64 v[4:5], v[218:219], 1, v[0:1]
	v_add_co_u32_e32 v0, vcc, 0x2000, v4
	s_mov_b64 s[16:17], 0x2400
	s_nop 0
	v_addc_co_u32_e32 v1, vcc, 0, v5, vcc
	global_load_dwordx4 v[0:3], v[0:1], off offset:1024
	v_lshl_add_u64 v[4:5], v[4:5], 0, s[16:17]
	s_and_b64 vcc, exec, s[40:41]
	s_cbranch_vccnz .LBB0_270
	global_load_dwordx4 v[12:15], v[4:5], off offset:2048
.LBB0_270:
	global_load_dwordx4 v[8:11], v[4:5], off offset:256
	s_and_b64 vcc, exec, s[40:41]
	s_cbranch_vccnz .LBB0_272
	global_load_dwordx4 v[194:197], v[4:5], off offset:2304
.LBB0_272:
	v_add_u32_e32 v224, 0x90, v220
	v_mov_b64_e32 v[4:5], s[94:95]
	v_mad_i64_i32 v[4:5], s[16:17], v224, s66, v[4:5]
	v_lshl_add_u64 v[4:5], s[14:15], 1, v[4:5]
	v_lshl_add_u64 v[4:5], v[218:219], 1, v[4:5]
	v_add_co_u32_e32 v6, vcc, 0x2000, v4
	s_mov_b64 s[16:17], 0x2400
	s_nop 0
	v_addc_co_u32_e32 v7, vcc, 0, v5, vcc
	global_load_dwordx4 v[190:193], v[6:7], off offset:1024
	v_lshl_add_u64 v[4:5], v[4:5], 0, s[16:17]
	s_and_b64 vcc, exec, s[40:41]
	s_cbranch_vccnz .LBB0_274
	global_load_dwordx4 v[186:189], v[4:5], off offset:2048

.LBB0_276:
	v_add_u32_e32 v222, 0xa0, v220
	v_mov_b64_e32 v[4:5], s[94:95]
	v_mad_i64_i32 v[4:5], s[16:17], v222, s66, v[4:5]
	v_lshl_add_u64 v[4:5], s[14:15], 1, v[4:5]
	v_lshl_add_u64 v[4:5], v[218:219], 1, v[4:5]
	v_add_co_u32_e32 v6, vcc, 0x2000, v4
	s_mov_b64 s[16:17], 0x2400
	s_nop 0
	v_addc_co_u32_e32 v7, vcc, 0, v5, vcc
	global_load_dwordx4 v[174:177], v[6:7], off offset:1024
	v_lshl_add_u64 v[4:5], v[4:5], 0, s[16:17]
	s_and_b64 vcc, exec, s[40:41]
	s_cbranch_vccnz .LBB0_278
	global_load_dwordx4 v[170:173], v[4:5], off offset:2048

.LBB0_280:
	v_add_u32_e32 v220, 0xb0, v220
	v_mov_b64_e32 v[4:5], s[94:95]
	v_mad_i64_i32 v[4:5], s[16:17], v220, s66, v[4:5]
	v_lshl_add_u64 v[4:5], s[14:15], 1, v[4:5]
	v_lshl_add_u64 v[4:5], v[218:219], 1, v[4:5]
	v_add_co_u32_e32 v6, vcc, 0x2000, v4
	s_mov_b64 s[14:15], 0x2400
	s_nop 0
	v_addc_co_u32_e32 v7, vcc, 0, v5, vcc
	global_load_dwordx4 v[158:161], v[6:7], off offset:1024
	v_lshl_add_u64 v[4:5], v[4:5], 0, s[14:15]
	s_and_b64 vcc, exec, s[40:41]
	s_cbranch_vccnz .LBB0_282
	global_load_dwordx4 v[154:157], v[4:5], off offset:2048
